# GEMM super-phase: setprio 0 issued two MFMAs before the block end, closing barrier directly behind the last MFMA
# speedup vs baseline: 1.0782x; 1.0058x over previous
; #define PG8_STAGE(bufoff, gbase, voff) do { _Pragma("unroll") for (int _i = 0; _i < 2; ++_i) \
;         __builtin_amdgcn_global_load_lds((const unsigned*)((const char*)(gbase) + (voff)[_i]), (PG8_LAS unsigned*)(lds + (bufoff) + ldsw + _i * 8192), 16, 0, 0); } while (0)
; #define PG8_LDA(dst, b, h) do { _Pragma("unroll") for (int m = 0; m < 4; ++m) _Pragma("unroll") for (int k = 0; k < 2; ++k) dst[m][k] = *(const PG8_LAS bf16x8*)(lds + PG8_SA(b, h) + aoff + m * 2048 + k * 1024); } while (0)
; #define PG8_LDB(dst, b, h) do { _Pragma("unroll") for (int n = 0; n < 2; ++n) _Pragma("unroll") for (int k = 0; k < 2; ++k) dst[n][k] = *(const PG8_LAS bf16x8*)(lds + PG8_SB(b, h) + boff + n * 2048 + k * 1024); } while (0)
; #define PG8_MMA(ai, bj, At, Bt) do { __builtin_amdgcn_s_setprio(1); _Pragma("unroll") for (int m = 0; m < 4; ++m) _Pragma("unroll") for (int n = 0; n < 2; ++n) _Pragma("unroll") for (int k = 0; k < 2; ++k) \
;         acc[ai][bj][m][n] = __builtin_amdgcn_mfma_f32_16x16x32_bf16(Bt[n][k], At[m][k], acc[ai][bj][m][n], 0, 0, 0); __builtin_amdgcn_s_setprio(0); } while (0)
; #define PG8_WAIT_V(n) asm volatile("s_waitcnt vmcnt(" #n ")" ::: "memory")
; #define PG8_WAIT_L(n) asm volatile("s_waitcnt lgkmcnt(" #n ")" ::: "memory")
; #define PG8_BAR __builtin_amdgcn_s_barrier()
; #define PG8_SCHED __builtin_amdgcn_sched_barrier(0)
; template <class Epi, class Sched, bool ALIGN_EPI = false, bool SP2 = false>
; __device__ __forceinline__ void gemm_phase(PG8_LAS unsigned char* lds, const Gemm g, const Sched& S, const Epi& E, const int tid) {
;     ...
;             const char* a2 = last ? nA : cA + (size_t)(t + 2) * kstep; const char* b2 = last ? nB : cB + (size_t)(t + 2) * kstep;
;             const char* a3 = a2 + kstep; const char* b3 = b2 + kstep;
;             if (last && has_next) S.a_ready(nxt);
;             if constexpr (SP2) {
;             PG8_LDB(B0, 0, 0); PG8_LDB(B1, 0, 1); PG8_SCHED; PG8_LDA(At, 0, 0); PG8_STAGE(PG8_SA(1, 1), a1 + hstep, voffA);
;             PG8_WAIT_V(8); PG8_WAIT_L(0); PG8_BAR; PG8_MMA(0, 0, At, B0); PG8_MMA(0, 1, At, B1); PG8_BAR; PG8_SCHED;
;             PG8_LDA(At, 0, 1); PG8_STAGE(PG8_SB(0, 0), b2, voffB); PG8_STAGE(PG8_SB(0, 1), b2 + hstep, voffB); PG8_STAGE(PG8_SA(0, 0), a2, voffA);
;             PG8_WAIT_V(8); PG8_WAIT_L(0); PG8_BAR; PG8_MMA(1, 0, At, B0); PG8_MMA(1, 1, At, B1); PG8_BAR; PG8_SCHED;
.LBB0_87:
	s_add_u32 s38, s22, s68
	s_addc_u32 s39, s23, s69
	s_add_u32 s38, s38, 0x100
	s_addc_u32 s39, s39, 0
	s_add_u32 s50, s89, s68
	s_addc_u32 s51, s90, s69
	s_add_i32 s92, 0, 0x10000
	s_cmpk_eq_i32 s68, 0x700
	s_cselect_b32 s73, s15, s39
	s_cselect_b32 s72, s86, s38
	v_add_u32_e32 v150, s92, v153
	s_cselect_b32 s71, s87, s51
	s_cselect_b32 s70, s88, s50
	s_add_i32 s38, 0, 0x14000
	ds_read_b128 v[170:173], v150
	ds_read_b128 v[174:177], v150 offset:1024
	ds_read_b128 v[178:181], v150 offset:2048
	ds_read_b128 v[182:185], v150 offset:3072
	v_add_u32_e32 v150, s38, v153
	ds_read_b128 v[186:189], v150
	ds_read_b128 v[190:193], v150 offset:1024
	ds_read_b128 v[206:209], v150 offset:2048
	ds_read_b128 v[210:213], v150 offset:3072
	v_lshl_add_u64 v[246:247], v[146:147], 0, s[68:69]
	s_add_i32 m0, s76, 0xc000
	ds_read_b128 v[214:217], v167
	ds_read_b128 v[218:221], v167 offset:1024
	ds_read_b128 v[222:225], v167 offset:2048
	ds_read_b128 v[226:229], v167 offset:3072
	ds_read_b128 v[230:233], v167 offset:4096
	ds_read_b128 v[234:237], v167 offset:5120
	ds_read_b128 v[238:241], v167 offset:6144
	ds_read_b128 v[242:245], v167 offset:7168
	global_load_lds_dwordx4 v[246:247], off
	v_lshl_add_u64 v[246:247], v[148:149], 0, s[68:69]
	s_add_i32 m0, s76, 0xe000
	s_nop 0
	global_load_lds_dwordx4 v[246:247], off
	s_waitcnt vmcnt(8)
	s_waitcnt lgkmcnt(0)
	s_setprio 1
	s_barrier
	v_mfma_f32_16x16x32_bf16 v[126:129], v[170:173], v[214:217], v[126:129]
	v_mfma_f32_16x16x32_bf16 v[122:125], v[178:181], v[214:217], v[122:125]
	v_mfma_f32_16x16x32_bf16 v[110:113], v[170:173], v[222:225], v[110:113]
	v_mfma_f32_16x16x32_bf16 v[106:109], v[178:181], v[222:225], v[106:109]
	v_mfma_f32_16x16x32_bf16 v[94:97], v[170:173], v[230:233], v[94:97]
	v_mfma_f32_16x16x32_bf16 v[90:93], v[178:181], v[230:233], v[90:93]
	v_mfma_f32_16x16x32_bf16 v[78:81], v[170:173], v[238:241], v[78:81]
	v_mfma_f32_16x16x32_bf16 v[74:77], v[178:181], v[238:241], v[74:77]
	v_mfma_f32_16x16x32_bf16 v[126:129], v[174:177], v[218:221], v[126:129]
	v_mfma_f32_16x16x32_bf16 v[122:125], v[182:185], v[218:221], v[122:125]
	v_mfma_f32_16x16x32_bf16 v[110:113], v[174:177], v[226:229], v[110:113]
	v_mfma_f32_16x16x32_bf16 v[106:109], v[182:185], v[226:229], v[106:109]
	v_mfma_f32_16x16x32_bf16 v[94:97], v[174:177], v[234:237], v[94:97]
	v_mfma_f32_16x16x32_bf16 v[90:93], v[182:185], v[234:237], v[90:93]
	v_mfma_f32_16x16x32_bf16 v[78:81], v[174:177], v[242:245], v[78:81]
	v_mfma_f32_16x16x32_bf16 v[74:77], v[182:185], v[242:245], v[74:77]
	v_mfma_f32_16x16x32_bf16 v[118:121], v[186:189], v[214:217], v[118:121]
	v_mfma_f32_16x16x32_bf16 v[114:117], v[206:209], v[214:217], v[114:117]
	v_mfma_f32_16x16x32_bf16 v[102:105], v[186:189], v[222:225], v[102:105]
	v_mfma_f32_16x16x32_bf16 v[98:101], v[206:209], v[222:225], v[98:101]
	v_mfma_f32_16x16x32_bf16 v[86:89], v[186:189], v[230:233], v[86:89]
	v_mfma_f32_16x16x32_bf16 v[82:85], v[206:209], v[230:233], v[82:85]
	v_mfma_f32_16x16x32_bf16 v[70:73], v[186:189], v[238:241], v[70:73]
	v_mfma_f32_16x16x32_bf16 v[66:69], v[206:209], v[238:241], v[66:69]
	v_mfma_f32_16x16x32_bf16 v[118:121], v[190:193], v[218:221], v[118:121]
	v_mfma_f32_16x16x32_bf16 v[114:117], v[210:213], v[218:221], v[114:117]
	v_mfma_f32_16x16x32_bf16 v[102:105], v[190:193], v[226:229], v[102:105]
	v_mfma_f32_16x16x32_bf16 v[98:101], v[210:213], v[226:229], v[98:101]
	v_mfma_f32_16x16x32_bf16 v[86:89], v[190:193], v[234:237], v[86:89]
	v_mfma_f32_16x16x32_bf16 v[82:85], v[210:213], v[234:237], v[82:85]
	s_setprio 0
	v_mfma_f32_16x16x32_bf16 v[70:73], v[190:193], v[242:245], v[70:73]
	v_mfma_f32_16x16x32_bf16 v[66:69], v[210:213], v[242:245], v[66:69]
	s_barrier
	s_add_i32 s39, s92, s75
	v_lshl_add_u64 v[246:247], s[70:71], 0, v[0:1]
	s_mov_b32 m0, s39
	ds_read_b128 v[214:217], v167 offset:16384
	ds_read_b128 v[218:221], v167 offset:17408
	ds_read_b128 v[222:225], v167 offset:18432
	ds_read_b128 v[226:229], v167 offset:19456
	ds_read_b128 v[230:233], v167 offset:20480
	ds_read_b128 v[234:237], v167 offset:21504
	ds_read_b128 v[238:241], v167 offset:22528
	ds_read_b128 v[242:245], v167 offset:23552
	global_load_lds_dwordx4 v[246:247], off
	s_add_i32 m0, s39, 0x2000
	s_add_u32 s50, s70, 0x40000
	v_lshl_add_u64 v[248:249], s[70:71], 0, v[130:131]
	s_addc_u32 s51, s71, 0
	s_add_i32 s38, s38, s75
	global_load_lds_dwordx4 v[248:249], off
	v_lshl_add_u64 v[250:251], s[50:51], 0, v[0:1]
	s_mov_b32 m0, s38
	v_lshl_add_u64 v[252:253], s[72:73], 0, v[132:133]
	global_load_lds_dwordx4 v[250:251], off
	v_lshl_add_u64 v[250:251], s[50:51], 0, v[130:131]
	s_add_i32 m0, s38, 0x2000
	s_nop 0
	global_load_lds_dwordx4 v[250:251], off
	v_lshl_add_u64 v[250:251], s[72:73], 0, v[134:135]
	s_mov_b32 m0, s76
	s_nop 0
	global_load_lds_dwordx4 v[250:251], off
	s_mov_b32 m0, s77
	s_nop 0
	global_load_lds_dwordx4 v[252:253], off
	s_waitcnt vmcnt(8)
	s_waitcnt lgkmcnt(0)
	s_setprio 1
	s_barrier
; #define PG8_STAGE(bufoff, gbase, voff) do { _Pragma("unroll") for (int _i = 0; _i < 2; ++_i) \
;         __builtin_amdgcn_global_load_lds((const unsigned*)((const char*)(gbase) + (voff)[_i]), (PG8_LAS unsigned*)(lds + (bufoff) + ldsw + _i * 8192), 16, 0, 0); } while (0)
; #define PG8_LDA(dst, b, h) do { _Pragma("unroll") for (int m = 0; m < 4; ++m) _Pragma("unroll") for (int k = 0; k < 2; ++k) dst[m][k] = *(const PG8_LAS bf16x8*)(lds + PG8_SA(b, h) + aoff + m * 2048 + k * 1024); } while (0)
; #define PG8_LDB(dst, b, h) do { _Pragma("unroll") for (int n = 0; n < 2; ++n) _Pragma("unroll") for (int k = 0; k < 2; ++k) dst[n][k] = *(const PG8_LAS bf16x8*)(lds + PG8_SB(b, h) + boff + n * 2048 + k * 1024); } while (0)
; #define PG8_MMA(ai, bj, At, Bt) do { __builtin_amdgcn_s_setprio(1); _Pragma("unroll") for (int m = 0; m < 4; ++m) _Pragma("unroll") for (int n = 0; n < 2; ++n) _Pragma("unroll") for (int k = 0; k < 2; ++k) \
;         acc[ai][bj][m][n] = __builtin_amdgcn_mfma_f32_16x16x32_bf16(Bt[n][k], At[m][k], acc[ai][bj][m][n], 0, 0, 0); __builtin_amdgcn_s_setprio(0); } while (0)
; #define PG8_WAIT_V(n) asm volatile("s_waitcnt vmcnt(" #n ")" ::: "memory")
; #define PG8_WAIT_L(n) asm volatile("s_waitcnt lgkmcnt(" #n ")" ::: "memory")
; #define PG8_BAR __builtin_amdgcn_s_barrier()
; #define PG8_SCHED __builtin_amdgcn_sched_barrier(0)
; template <class Epi, class Sched, bool ALIGN_EPI = false, bool SP2 = false>
; __device__ __forceinline__ void gemm_phase(PG8_LAS unsigned char* lds, const Gemm g, const Sched& S, const Epi& E, const int tid) {
;     ...
;             PG8_WAIT_V(8); PG8_WAIT_L(0); PG8_BAR; PG8_MMA(1, 0, At, B0); PG8_MMA(1, 1, At, B1); PG8_BAR; PG8_SCHED;
;             PG8_LDB(B0, 1, 0); PG8_LDB(B1, 1, 1); PG8_SCHED; PG8_LDA(At, 1, 0); PG8_STAGE(PG8_SA(0, 1), a2 + hstep, voffA);
;             PG8_WAIT_V(8); PG8_WAIT_L(0); PG8_BAR; PG8_MMA(0, 0, At, B0); PG8_MMA(0, 1, At, B1); PG8_BAR; PG8_SCHED;
	v_mfma_f32_16x16x32_bf16 v[62:65], v[170:173], v[214:217], v[62:65]
	v_mfma_f32_16x16x32_bf16 v[58:61], v[178:181], v[214:217], v[58:61]
	v_mfma_f32_16x16x32_bf16 v[46:49], v[170:173], v[222:225], v[46:49]
	v_mfma_f32_16x16x32_bf16 v[42:45], v[178:181], v[222:225], v[42:45]
	v_mfma_f32_16x16x32_bf16 v[30:33], v[170:173], v[230:233], v[30:33]
	v_mfma_f32_16x16x32_bf16 v[26:29], v[178:181], v[230:233], v[26:29]
	v_mfma_f32_16x16x32_bf16 v[14:17], v[170:173], v[238:241], v[14:17]
	v_mfma_f32_16x16x32_bf16 v[10:13], v[178:181], v[238:241], v[10:13]
	v_mfma_f32_16x16x32_bf16 v[62:65], v[174:177], v[218:221], v[62:65]
	v_mfma_f32_16x16x32_bf16 v[58:61], v[182:185], v[218:221], v[58:61]
	v_mfma_f32_16x16x32_bf16 v[46:49], v[174:177], v[226:229], v[46:49]
	v_mfma_f32_16x16x32_bf16 v[42:45], v[182:185], v[226:229], v[42:45]
	v_mfma_f32_16x16x32_bf16 v[30:33], v[174:177], v[234:237], v[30:33]
	v_mfma_f32_16x16x32_bf16 v[26:29], v[182:185], v[234:237], v[26:29]
	v_mfma_f32_16x16x32_bf16 v[14:17], v[174:177], v[242:245], v[14:17]
	v_mfma_f32_16x16x32_bf16 v[10:13], v[182:185], v[242:245], v[10:13]
	v_mfma_f32_16x16x32_bf16 v[54:57], v[186:189], v[214:217], v[54:57]
	v_mfma_f32_16x16x32_bf16 v[50:53], v[206:209], v[214:217], v[50:53]
	v_mfma_f32_16x16x32_bf16 v[38:41], v[186:189], v[222:225], v[38:41]
	v_mfma_f32_16x16x32_bf16 v[34:37], v[206:209], v[222:225], v[34:37]
	v_mfma_f32_16x16x32_bf16 v[22:25], v[186:189], v[230:233], v[22:25]
	v_mfma_f32_16x16x32_bf16 v[18:21], v[206:209], v[230:233], v[18:21]
	v_mfma_f32_16x16x32_bf16 v[6:9], v[186:189], v[238:241], v[6:9]
	v_mfma_f32_16x16x32_bf16 v[2:5], v[206:209], v[238:241], v[2:5]
	v_mfma_f32_16x16x32_bf16 v[54:57], v[190:193], v[218:221], v[54:57]
	v_mfma_f32_16x16x32_bf16 v[50:53], v[210:213], v[218:221], v[50:53]
	v_mfma_f32_16x16x32_bf16 v[38:41], v[190:193], v[226:229], v[38:41]
	v_mfma_f32_16x16x32_bf16 v[34:37], v[210:213], v[226:229], v[34:37]
	v_mfma_f32_16x16x32_bf16 v[22:25], v[190:193], v[234:237], v[22:25]
	v_mfma_f32_16x16x32_bf16 v[18:21], v[210:213], v[234:237], v[18:21]
	s_setprio 0
	v_mfma_f32_16x16x32_bf16 v[6:9], v[190:193], v[242:245], v[6:9]
	v_mfma_f32_16x16x32_bf16 v[2:5], v[210:213], v[242:245], v[2:5]
	s_barrier
	s_add_i32 s38, 0, 0x18000
	v_add_u32_e32 v150, s38, v153
	s_add_i32 s39, 0, 0x1c000
	ds_read_b128 v[170:173], v150
	ds_read_b128 v[174:177], v150 offset:1024
	ds_read_b128 v[178:181], v150 offset:2048
	ds_read_b128 v[182:185], v150 offset:3072
	v_add_u32_e32 v150, s39, v153
	ds_read_b128 v[186:189], v150
	ds_read_b128 v[190:193], v150 offset:1024
	ds_read_b128 v[206:209], v150 offset:2048
	ds_read_b128 v[210:213], v150 offset:3072
	s_add_u32 s50, s72, 0x40000
	s_addc_u32 s51, s73, 0
	s_mov_b32 m0, s78
	v_lshl_add_u64 v[194:195], s[50:51], 0, v[134:135]
	ds_read_b128 v[214:217], v167 offset:32768
	ds_read_b128 v[218:221], v167 offset:33792
	ds_read_b128 v[222:225], v167 offset:34816
	ds_read_b128 v[226:229], v167 offset:35840
	ds_read_b128 v[230:233], v167 offset:36864
	ds_read_b128 v[234:237], v167 offset:37888
	ds_read_b128 v[238:241], v167 offset:38912
	ds_read_b128 v[242:245], v167 offset:39936
	global_load_lds_dwordx4 v[194:195], off
	v_lshl_add_u64 v[194:195], s[50:51], 0, v[132:133]
	s_mov_b32 m0, s79
	s_nop 0
	global_load_lds_dwordx4 v[194:195], off
	s_waitcnt vmcnt(8)
	s_waitcnt lgkmcnt(0)
	s_setprio 1
	s_barrier
	v_mfma_f32_16x16x32_bf16 v[126:129], v[170:173], v[214:217], v[126:129]
	v_mfma_f32_16x16x32_bf16 v[122:125], v[178:181], v[214:217], v[122:125]
	v_mfma_f32_16x16x32_bf16 v[110:113], v[170:173], v[222:225], v[110:113]
	v_mfma_f32_16x16x32_bf16 v[106:109], v[178:181], v[222:225], v[106:109]
	v_mfma_f32_16x16x32_bf16 v[94:97], v[170:173], v[230:233], v[94:97]
	v_mfma_f32_16x16x32_bf16 v[90:93], v[178:181], v[230:233], v[90:93]
	v_mfma_f32_16x16x32_bf16 v[78:81], v[170:173], v[238:241], v[78:81]
	v_mfma_f32_16x16x32_bf16 v[74:77], v[178:181], v[238:241], v[74:77]
	v_mfma_f32_16x16x32_bf16 v[126:129], v[174:177], v[218:221], v[126:129]
	v_mfma_f32_16x16x32_bf16 v[122:125], v[182:185], v[218:221], v[122:125]
	v_mfma_f32_16x16x32_bf16 v[110:113], v[174:177], v[226:229], v[110:113]
	v_mfma_f32_16x16x32_bf16 v[106:109], v[182:185], v[226:229], v[106:109]
	v_mfma_f32_16x16x32_bf16 v[94:97], v[174:177], v[234:237], v[94:97]
	v_mfma_f32_16x16x32_bf16 v[90:93], v[182:185], v[234:237], v[90:93]
	v_mfma_f32_16x16x32_bf16 v[78:81], v[174:177], v[242:245], v[78:81]
	v_mfma_f32_16x16x32_bf16 v[74:77], v[182:185], v[242:245], v[74:77]
	v_mfma_f32_16x16x32_bf16 v[118:121], v[186:189], v[214:217], v[118:121]
	v_mfma_f32_16x16x32_bf16 v[114:117], v[206:209], v[214:217], v[114:117]
	v_mfma_f32_16x16x32_bf16 v[102:105], v[186:189], v[222:225], v[102:105]
	v_mfma_f32_16x16x32_bf16 v[98:101], v[206:209], v[222:225], v[98:101]
	v_mfma_f32_16x16x32_bf16 v[86:89], v[186:189], v[230:233], v[86:89]
	v_mfma_f32_16x16x32_bf16 v[82:85], v[206:209], v[230:233], v[82:85]
	v_mfma_f32_16x16x32_bf16 v[70:73], v[186:189], v[238:241], v[70:73]
	v_mfma_f32_16x16x32_bf16 v[66:69], v[206:209], v[238:241], v[66:69]
	v_mfma_f32_16x16x32_bf16 v[118:121], v[190:193], v[218:221], v[118:121]
	v_mfma_f32_16x16x32_bf16 v[114:117], v[210:213], v[218:221], v[114:117]
	v_mfma_f32_16x16x32_bf16 v[102:105], v[190:193], v[226:229], v[102:105]
	v_mfma_f32_16x16x32_bf16 v[98:101], v[210:213], v[226:229], v[98:101]
	v_mfma_f32_16x16x32_bf16 v[86:89], v[190:193], v[234:237], v[86:89]
	v_mfma_f32_16x16x32_bf16 v[82:85], v[210:213], v[234:237], v[82:85]
	s_setprio 0
	v_mfma_f32_16x16x32_bf16 v[70:73], v[190:193], v[242:245], v[70:73]
	v_mfma_f32_16x16x32_bf16 v[66:69], v[210:213], v[242:245], v[66:69]
	s_barrier
; #define PG8_STAGE(bufoff, gbase, voff) do { _Pragma("unroll") for (int _i = 0; _i < 2; ++_i) \
;         __builtin_amdgcn_global_load_lds((const unsigned*)((const char*)(gbase) + (voff)[_i]), (PG8_LAS unsigned*)(lds + (bufoff) + ldsw + _i * 8192), 16, 0, 0); } while (0)
; #define PG8_LDA(dst, b, h) do { _Pragma("unroll") for (int m = 0; m < 4; ++m) _Pragma("unroll") for (int k = 0; k < 2; ++k) dst[m][k] = *(const PG8_LAS bf16x8*)(lds + PG8_SA(b, h) + aoff + m * 2048 + k * 1024); } while (0)
; #define PG8_MMA(ai, bj, At, Bt) do { __builtin_amdgcn_s_setprio(1); _Pragma("unroll") for (int m = 0; m < 4; ++m) _Pragma("unroll") for (int n = 0; n < 2; ++n) _Pragma("unroll") for (int k = 0; k < 2; ++k) \
;         acc[ai][bj][m][n] = __builtin_amdgcn_mfma_f32_16x16x32_bf16(Bt[n][k], At[m][k], acc[ai][bj][m][n], 0, 0, 0); __builtin_amdgcn_s_setprio(0); } while (0)
; #define PG8_WAIT_V(n) asm volatile("s_waitcnt vmcnt(" #n ")" ::: "memory")
; #define PG8_WAIT_L(n) asm volatile("s_waitcnt lgkmcnt(" #n ")" ::: "memory")
; #define PG8_BAR __builtin_amdgcn_s_barrier()
; #define PG8_SCHED __builtin_amdgcn_sched_barrier(0)
; template <class Epi, class Sched, bool ALIGN_EPI = false, bool SP2 = false>
; __device__ __forceinline__ void gemm_phase(PG8_LAS unsigned char* lds, const Gemm g, const Sched& S, const Epi& E, const int tid) {
;     ...
;             PG8_WAIT_V(8); PG8_WAIT_L(0); PG8_BAR; PG8_MMA(0, 0, At, B0); PG8_MMA(0, 1, At, B1); PG8_BAR; PG8_SCHED;
;             PG8_LDA(At, 1, 1); PG8_STAGE(PG8_SB(1, 0), b3, voffB); PG8_STAGE(PG8_SB(1, 1), b3 + hstep, voffB); PG8_STAGE(PG8_SA(1, 0), a3, voffA);
;             PG8_WAIT_V(8); PG8_WAIT_L(0); PG8_BAR; PG8_MMA(1, 0, At, B0); PG8_MMA(1, 1, At, B1); PG8_BAR; PG8_SCHED;
	s_add_i32 s38, s38, s75
	v_lshl_add_u64 v[194:195], v[246:247], 0, s[56:57]
	s_mov_b32 m0, s38
	ds_read_b128 v[214:217], v167 offset:49152
	ds_read_b128 v[218:221], v167 offset:50176
	ds_read_b128 v[222:225], v167 offset:51200
	ds_read_b128 v[226:229], v167 offset:52224
	ds_read_b128 v[230:233], v167 offset:53248
	ds_read_b128 v[234:237], v167 offset:54272
	ds_read_b128 v[238:241], v167 offset:55296
	ds_read_b128 v[242:245], v167 offset:56320
	global_load_lds_dwordx4 v[194:195], off
	s_add_i32 m0, s38, 0x2000
	s_add_u32 s50, s70, 0x40080
	v_lshl_add_u64 v[194:195], v[248:249], 0, s[56:57]
	s_addc_u32 s51, s71, 0
	s_add_i32 s38, s39, s75
	global_load_lds_dwordx4 v[194:195], off
	v_lshl_add_u64 v[194:195], s[50:51], 0, v[0:1]
	s_mov_b32 m0, s38
	s_nop 0
	global_load_lds_dwordx4 v[194:195], off
	v_lshl_add_u64 v[194:195], s[50:51], 0, v[130:131]
	s_add_i32 m0, s38, 0x2000
	s_nop 0
	global_load_lds_dwordx4 v[194:195], off
	v_lshl_add_u64 v[194:195], v[250:251], 0, s[56:57]
	s_mov_b32 m0, s80
	s_nop 0
	global_load_lds_dwordx4 v[194:195], off
	v_lshl_add_u64 v[194:195], v[252:253], 0, s[56:57]
	s_mov_b32 m0, s81
	s_nop 0
	global_load_lds_dwordx4 v[194:195], off
	s_waitcnt vmcnt(8)
	s_waitcnt lgkmcnt(0)
	s_setprio 1
	s_barrier
	v_mfma_f32_16x16x32_bf16 v[62:65], v[170:173], v[214:217], v[62:65]
	v_mfma_f32_16x16x32_bf16 v[58:61], v[178:181], v[214:217], v[58:61]
	v_mfma_f32_16x16x32_bf16 v[46:49], v[170:173], v[222:225], v[46:49]
	v_mfma_f32_16x16x32_bf16 v[42:45], v[178:181], v[222:225], v[42:45]
	v_mfma_f32_16x16x32_bf16 v[30:33], v[170:173], v[230:233], v[30:33]
	v_mfma_f32_16x16x32_bf16 v[26:29], v[178:181], v[230:233], v[26:29]
	v_mfma_f32_16x16x32_bf16 v[14:17], v[170:173], v[238:241], v[14:17]
	v_mfma_f32_16x16x32_bf16 v[10:13], v[178:181], v[238:241], v[10:13]
	v_mfma_f32_16x16x32_bf16 v[62:65], v[174:177], v[218:221], v[62:65]
	v_mfma_f32_16x16x32_bf16 v[58:61], v[182:185], v[218:221], v[58:61]
	v_mfma_f32_16x16x32_bf16 v[46:49], v[174:177], v[226:229], v[46:49]
	v_mfma_f32_16x16x32_bf16 v[42:45], v[182:185], v[226:229], v[42:45]
	v_mfma_f32_16x16x32_bf16 v[30:33], v[174:177], v[234:237], v[30:33]
	v_mfma_f32_16x16x32_bf16 v[26:29], v[182:185], v[234:237], v[26:29]
	v_mfma_f32_16x16x32_bf16 v[14:17], v[174:177], v[242:245], v[14:17]
	v_mfma_f32_16x16x32_bf16 v[10:13], v[182:185], v[242:245], v[10:13]
	v_mfma_f32_16x16x32_bf16 v[54:57], v[186:189], v[214:217], v[54:57]
	v_mfma_f32_16x16x32_bf16 v[50:53], v[206:209], v[214:217], v[50:53]
	v_mfma_f32_16x16x32_bf16 v[38:41], v[186:189], v[222:225], v[38:41]
	v_mfma_f32_16x16x32_bf16 v[34:37], v[206:209], v[222:225], v[34:37]
	v_mfma_f32_16x16x32_bf16 v[22:25], v[186:189], v[230:233], v[22:25]
	v_mfma_f32_16x16x32_bf16 v[18:21], v[206:209], v[230:233], v[18:21]
	v_mfma_f32_16x16x32_bf16 v[6:9], v[186:189], v[238:241], v[6:9]
	v_mfma_f32_16x16x32_bf16 v[2:5], v[206:209], v[238:241], v[2:5]
	v_mfma_f32_16x16x32_bf16 v[54:57], v[190:193], v[218:221], v[54:57]
	v_mfma_f32_16x16x32_bf16 v[50:53], v[210:213], v[218:221], v[50:53]
	v_mfma_f32_16x16x32_bf16 v[38:41], v[190:193], v[226:229], v[38:41]
	v_mfma_f32_16x16x32_bf16 v[34:37], v[210:213], v[226:229], v[34:37]
	v_mfma_f32_16x16x32_bf16 v[22:25], v[190:193], v[234:237], v[22:25]
	v_mfma_f32_16x16x32_bf16 v[18:21], v[210:213], v[234:237], v[18:21]
	s_setprio 0
	v_mfma_f32_16x16x32_bf16 v[6:9], v[190:193], v[242:245], v[6:9]
	v_mfma_f32_16x16x32_bf16 v[2:5], v[210:213], v[242:245], v[2:5]
	s_barrier
	s_add_i32 s91, s91, 2
	s_add_u32 s68, s68, 0x100
	s_addc_u32 s69, s69, 0
	s_cmp_gt_u32 s91, 13
	s_cbranch_scc1 .LBB0_90

; #define PG8_STAGE(bufoff, gbase, voff) do { _Pragma("unroll") for (int _i = 0; _i < 2; ++_i) \
;         __builtin_amdgcn_global_load_lds((const unsigned*)((const char*)(gbase) + (voff)[_i]), (PG8_LAS unsigned*)(lds + (bufoff) + ldsw + _i * 8192), 16, 0, 0); } while (0)
; #define PG8_LDA(dst, b, h) do { _Pragma("unroll") for (int m = 0; m < 4; ++m) _Pragma("unroll") for (int k = 0; k < 2; ++k) dst[m][k] = *(const PG8_LAS bf16x8*)(lds + PG8_SA(b, h) + aoff + m * 2048 + k * 1024); } while (0)
; #define PG8_LDB(dst, b, h) do { _Pragma("unroll") for (int n = 0; n < 2; ++n) _Pragma("unroll") for (int k = 0; k < 2; ++k) dst[n][k] = *(const PG8_LAS bf16x8*)(lds + PG8_SB(b, h) + boff + n * 2048 + k * 1024); } while (0)
; #define PG8_MMA(ai, bj, At, Bt) do { __builtin_amdgcn_s_setprio(1); _Pragma("unroll") for (int m = 0; m < 4; ++m) _Pragma("unroll") for (int n = 0; n < 2; ++n) _Pragma("unroll") for (int k = 0; k < 2; ++k) \
;         acc[ai][bj][m][n] = __builtin_amdgcn_mfma_f32_16x16x32_bf16(Bt[n][k], At[m][k], acc[ai][bj][m][n], 0, 0, 0); __builtin_amdgcn_s_setprio(0); } while (0)
; #define PG8_WAIT_V(n) asm volatile("s_waitcnt vmcnt(" #n ")" ::: "memory")
; #define PG8_WAIT_L(n) asm volatile("s_waitcnt lgkmcnt(" #n ")" ::: "memory")
; #define PG8_BAR __builtin_amdgcn_s_barrier()
; #define PG8_SCHED __builtin_amdgcn_sched_barrier(0)
; template <class Epi, class Sched, bool ALIGN_EPI = false, bool SP2 = false>
; __device__ __forceinline__ void gemm_phase(PG8_LAS unsigned char* lds, const Gemm g, const Sched& S, const Epi& E, const int tid) {
;     ...
;             const char* a2 = last ? nA : cA + (size_t)(t + 2) * kstep; const char* b2 = last ? nB : cB + (size_t)(t + 2) * kstep;
;             const char* a3 = a2 + kstep; const char* b3 = b2 + kstep;
;             if (last && has_next) S.a_ready(nxt);
;             if constexpr (SP2) {
;             PG8_LDB(B0, 0, 0); PG8_LDB(B1, 0, 1); PG8_SCHED; PG8_LDA(At, 0, 0); PG8_STAGE(PG8_SA(1, 1), a1 + hstep, voffA);
;             PG8_WAIT_V(8); PG8_WAIT_L(0); PG8_BAR; PG8_MMA(0, 0, At, B0); PG8_MMA(0, 1, At, B1); PG8_BAR; PG8_SCHED;
;             PG8_LDA(At, 0, 1); PG8_STAGE(PG8_SB(0, 0), b2, voffB); PG8_STAGE(PG8_SB(0, 1), b2 + hstep, voffB); PG8_STAGE(PG8_SA(0, 0), a2, voffA);
;             PG8_WAIT_V(8); PG8_WAIT_L(0); PG8_BAR; PG8_MMA(1, 0, At, B0); PG8_MMA(1, 1, At, B1); PG8_BAR; PG8_SCHED;
.LBB0_208:
	s_add_u32 s38, s10, s12
	s_addc_u32 s39, s11, s13
	s_add_u32 s38, s38, 0x100
	s_addc_u32 s39, s39, 0
	s_add_u32 s51, vcc_lo, s12
	s_addc_u32 s74, vcc_hi, s13
	s_add_i32 s59, 0, 0x10000
	s_cmpk_eq_i32 s12, 0x700
	s_cselect_b32 s77, s49, s39
	s_cselect_b32 s76, s78, s38
	v_add_u32_e32 v0, s59, v153
	s_cselect_b32 s75, s69, s74
	s_cselect_b32 s74, s79, s51
	s_add_i32 s51, 0, 0x14000
	ds_read_b128 v[170:173], v0
	ds_read_b128 v[174:177], v0 offset:1024
	ds_read_b128 v[178:181], v0 offset:2048
	ds_read_b128 v[182:185], v0 offset:3072
	v_add_u32_e32 v0, s51, v153
	ds_read_b128 v[186:189], v0
	ds_read_b128 v[190:193], v0 offset:1024
	ds_read_b128 v[206:209], v0 offset:2048
	ds_read_b128 v[210:213], v0 offset:3072
	v_lshl_add_u64 v[194:195], v[148:149], 0, s[12:13]
	s_add_i32 m0, s84, 0xc000
	ds_read_b128 v[214:217], v167
	ds_read_b128 v[218:221], v167 offset:1024
	ds_read_b128 v[222:225], v167 offset:2048
	ds_read_b128 v[226:229], v167 offset:3072
	ds_read_b128 v[230:233], v167 offset:4096
	ds_read_b128 v[234:237], v167 offset:5120
	ds_read_b128 v[238:241], v167 offset:6144
	ds_read_b128 v[242:245], v167 offset:7168
	global_load_lds_dwordx4 v[194:195], off
	v_lshl_add_u64 v[194:195], v[150:151], 0, s[12:13]
	s_add_i32 m0, s84, 0xe000
	s_nop 0
	global_load_lds_dwordx4 v[194:195], off
	s_waitcnt vmcnt(8)
	s_waitcnt lgkmcnt(0)
	s_setprio 1
	s_barrier
	v_mfma_f32_16x16x32_bf16 v[126:129], v[170:173], v[214:217], v[126:129]
	v_mfma_f32_16x16x32_bf16 v[122:125], v[178:181], v[214:217], v[122:125]
	v_mfma_f32_16x16x32_bf16 v[110:113], v[170:173], v[222:225], v[110:113]
	v_mfma_f32_16x16x32_bf16 v[106:109], v[178:181], v[222:225], v[106:109]
	v_mfma_f32_16x16x32_bf16 v[94:97], v[170:173], v[230:233], v[94:97]
	v_mfma_f32_16x16x32_bf16 v[90:93], v[178:181], v[230:233], v[90:93]
	v_mfma_f32_16x16x32_bf16 v[78:81], v[170:173], v[238:241], v[78:81]
	v_mfma_f32_16x16x32_bf16 v[74:77], v[178:181], v[238:241], v[74:77]
	v_mfma_f32_16x16x32_bf16 v[126:129], v[174:177], v[218:221], v[126:129]
	v_mfma_f32_16x16x32_bf16 v[122:125], v[182:185], v[218:221], v[122:125]
	v_mfma_f32_16x16x32_bf16 v[110:113], v[174:177], v[226:229], v[110:113]
	v_mfma_f32_16x16x32_bf16 v[106:109], v[182:185], v[226:229], v[106:109]
	v_mfma_f32_16x16x32_bf16 v[94:97], v[174:177], v[234:237], v[94:97]
	v_mfma_f32_16x16x32_bf16 v[90:93], v[182:185], v[234:237], v[90:93]
	v_mfma_f32_16x16x32_bf16 v[78:81], v[174:177], v[242:245], v[78:81]
	v_mfma_f32_16x16x32_bf16 v[74:77], v[182:185], v[242:245], v[74:77]
	v_mfma_f32_16x16x32_bf16 v[118:121], v[186:189], v[214:217], v[118:121]
	v_mfma_f32_16x16x32_bf16 v[114:117], v[206:209], v[214:217], v[114:117]
	v_mfma_f32_16x16x32_bf16 v[102:105], v[186:189], v[222:225], v[102:105]
	v_mfma_f32_16x16x32_bf16 v[98:101], v[206:209], v[222:225], v[98:101]
	v_mfma_f32_16x16x32_bf16 v[86:89], v[186:189], v[230:233], v[86:89]
	v_mfma_f32_16x16x32_bf16 v[82:85], v[206:209], v[230:233], v[82:85]
	v_mfma_f32_16x16x32_bf16 v[70:73], v[186:189], v[238:241], v[70:73]
	v_mfma_f32_16x16x32_bf16 v[66:69], v[206:209], v[238:241], v[66:69]
	v_mfma_f32_16x16x32_bf16 v[118:121], v[190:193], v[218:221], v[118:121]
	v_mfma_f32_16x16x32_bf16 v[114:117], v[210:213], v[218:221], v[114:117]
	v_mfma_f32_16x16x32_bf16 v[102:105], v[190:193], v[226:229], v[102:105]
	v_mfma_f32_16x16x32_bf16 v[98:101], v[210:213], v[226:229], v[98:101]
	v_mfma_f32_16x16x32_bf16 v[86:89], v[190:193], v[234:237], v[86:89]
	v_mfma_f32_16x16x32_bf16 v[82:85], v[210:213], v[234:237], v[82:85]
	s_setprio 0
	v_mfma_f32_16x16x32_bf16 v[70:73], v[190:193], v[242:245], v[70:73]
	v_mfma_f32_16x16x32_bf16 v[66:69], v[210:213], v[242:245], v[66:69]
	s_barrier
	s_add_i32 s38, s59, s83
	v_lshl_add_u64 v[194:195], s[74:75], 0, v[134:135]
	s_mov_b32 m0, s38
	ds_read_b128 v[214:217], v167 offset:16384
	ds_read_b128 v[218:221], v167 offset:17408
	ds_read_b128 v[222:225], v167 offset:18432
	ds_read_b128 v[226:229], v167 offset:19456
	ds_read_b128 v[230:233], v167 offset:20480
	ds_read_b128 v[234:237], v167 offset:21504
	ds_read_b128 v[238:241], v167 offset:22528
	ds_read_b128 v[242:245], v167 offset:23552
	global_load_lds_dwordx4 v[194:195], off
	s_add_i32 m0, s38, 0x2000
	s_add_u32 s38, s74, 0x40000
	v_lshl_add_u64 v[246:247], s[74:75], 0, v[130:131]
	s_addc_u32 s39, s75, 0
	s_add_i32 s51, s51, s83
	global_load_lds_dwordx4 v[246:247], off
	v_lshl_add_u64 v[248:249], s[38:39], 0, v[134:135]
	s_mov_b32 m0, s51
	v_lshl_add_u64 v[250:251], s[76:77], 0, v[132:133]
	global_load_lds_dwordx4 v[248:249], off
	v_lshl_add_u64 v[248:249], s[38:39], 0, v[130:131]
	s_add_i32 m0, s51, 0x2000
	s_nop 0
	global_load_lds_dwordx4 v[248:249], off
	v_lshl_add_u64 v[248:249], s[76:77], 0, v[136:137]
	s_mov_b32 m0, s84
	s_nop 0
	global_load_lds_dwordx4 v[248:249], off
	s_mov_b32 m0, s85
	s_nop 0
	global_load_lds_dwordx4 v[250:251], off
	s_waitcnt vmcnt(8)
	s_waitcnt lgkmcnt(0)
	s_setprio 1
	s_barrier
; #define PG8_STAGE(bufoff, gbase, voff) do { _Pragma("unroll") for (int _i = 0; _i < 2; ++_i) \
;         __builtin_amdgcn_global_load_lds((const unsigned*)((const char*)(gbase) + (voff)[_i]), (PG8_LAS unsigned*)(lds + (bufoff) + ldsw + _i * 8192), 16, 0, 0); } while (0)
; #define PG8_LDA(dst, b, h) do { _Pragma("unroll") for (int m = 0; m < 4; ++m) _Pragma("unroll") for (int k = 0; k < 2; ++k) dst[m][k] = *(const PG8_LAS bf16x8*)(lds + PG8_SA(b, h) + aoff + m * 2048 + k * 1024); } while (0)
; #define PG8_LDB(dst, b, h) do { _Pragma("unroll") for (int n = 0; n < 2; ++n) _Pragma("unroll") for (int k = 0; k < 2; ++k) dst[n][k] = *(const PG8_LAS bf16x8*)(lds + PG8_SB(b, h) + boff + n * 2048 + k * 1024); } while (0)
; #define PG8_MMA(ai, bj, At, Bt) do { __builtin_amdgcn_s_setprio(1); _Pragma("unroll") for (int m = 0; m < 4; ++m) _Pragma("unroll") for (int n = 0; n < 2; ++n) _Pragma("unroll") for (int k = 0; k < 2; ++k) \
;         acc[ai][bj][m][n] = __builtin_amdgcn_mfma_f32_16x16x32_bf16(Bt[n][k], At[m][k], acc[ai][bj][m][n], 0, 0, 0); __builtin_amdgcn_s_setprio(0); } while (0)
; #define PG8_WAIT_V(n) asm volatile("s_waitcnt vmcnt(" #n ")" ::: "memory")
; #define PG8_WAIT_L(n) asm volatile("s_waitcnt lgkmcnt(" #n ")" ::: "memory")
; #define PG8_BAR __builtin_amdgcn_s_barrier()
; #define PG8_SCHED __builtin_amdgcn_sched_barrier(0)
; template <class Epi, class Sched, bool ALIGN_EPI = false, bool SP2 = false>
; __device__ __forceinline__ void gemm_phase(PG8_LAS unsigned char* lds, const Gemm g, const Sched& S, const Epi& E, const int tid) {
;     ...
;             PG8_WAIT_V(8); PG8_WAIT_L(0); PG8_BAR; PG8_MMA(1, 0, At, B0); PG8_MMA(1, 1, At, B1); PG8_BAR; PG8_SCHED;
;             PG8_LDB(B0, 1, 0); PG8_LDB(B1, 1, 1); PG8_SCHED; PG8_LDA(At, 1, 0); PG8_STAGE(PG8_SA(0, 1), a2 + hstep, voffA);
;             PG8_WAIT_V(8); PG8_WAIT_L(0); PG8_BAR; PG8_MMA(0, 0, At, B0); PG8_MMA(0, 1, At, B1); PG8_BAR; PG8_SCHED;
	v_mfma_f32_16x16x32_bf16 v[62:65], v[170:173], v[214:217], v[62:65]
	v_mfma_f32_16x16x32_bf16 v[58:61], v[178:181], v[214:217], v[58:61]
	v_mfma_f32_16x16x32_bf16 v[46:49], v[170:173], v[222:225], v[46:49]
	v_mfma_f32_16x16x32_bf16 v[42:45], v[178:181], v[222:225], v[42:45]
	v_mfma_f32_16x16x32_bf16 v[30:33], v[170:173], v[230:233], v[30:33]
	v_mfma_f32_16x16x32_bf16 v[26:29], v[178:181], v[230:233], v[26:29]
	v_mfma_f32_16x16x32_bf16 v[14:17], v[170:173], v[238:241], v[14:17]
	v_mfma_f32_16x16x32_bf16 v[10:13], v[178:181], v[238:241], v[10:13]
	v_mfma_f32_16x16x32_bf16 v[62:65], v[174:177], v[218:221], v[62:65]
	v_mfma_f32_16x16x32_bf16 v[58:61], v[182:185], v[218:221], v[58:61]
	v_mfma_f32_16x16x32_bf16 v[46:49], v[174:177], v[226:229], v[46:49]
	v_mfma_f32_16x16x32_bf16 v[42:45], v[182:185], v[226:229], v[42:45]
	v_mfma_f32_16x16x32_bf16 v[30:33], v[174:177], v[234:237], v[30:33]
	v_mfma_f32_16x16x32_bf16 v[26:29], v[182:185], v[234:237], v[26:29]
	v_mfma_f32_16x16x32_bf16 v[14:17], v[174:177], v[242:245], v[14:17]
	v_mfma_f32_16x16x32_bf16 v[10:13], v[182:185], v[242:245], v[10:13]
	v_mfma_f32_16x16x32_bf16 v[54:57], v[186:189], v[214:217], v[54:57]
	v_mfma_f32_16x16x32_bf16 v[50:53], v[206:209], v[214:217], v[50:53]
	v_mfma_f32_16x16x32_bf16 v[38:41], v[186:189], v[222:225], v[38:41]
	v_mfma_f32_16x16x32_bf16 v[34:37], v[206:209], v[222:225], v[34:37]
	v_mfma_f32_16x16x32_bf16 v[22:25], v[186:189], v[230:233], v[22:25]
	v_mfma_f32_16x16x32_bf16 v[18:21], v[206:209], v[230:233], v[18:21]
	v_mfma_f32_16x16x32_bf16 v[6:9], v[186:189], v[238:241], v[6:9]
	v_mfma_f32_16x16x32_bf16 v[2:5], v[206:209], v[238:241], v[2:5]
	v_mfma_f32_16x16x32_bf16 v[54:57], v[190:193], v[218:221], v[54:57]
	v_mfma_f32_16x16x32_bf16 v[50:53], v[210:213], v[218:221], v[50:53]
	v_mfma_f32_16x16x32_bf16 v[38:41], v[190:193], v[226:229], v[38:41]
	v_mfma_f32_16x16x32_bf16 v[34:37], v[210:213], v[226:229], v[34:37]
	v_mfma_f32_16x16x32_bf16 v[22:25], v[190:193], v[234:237], v[22:25]
	v_mfma_f32_16x16x32_bf16 v[18:21], v[210:213], v[234:237], v[18:21]
	s_setprio 0
	v_mfma_f32_16x16x32_bf16 v[6:9], v[190:193], v[242:245], v[6:9]
	v_mfma_f32_16x16x32_bf16 v[2:5], v[210:213], v[242:245], v[2:5]
	s_barrier
	s_add_i32 s51, 0, 0x18000
	v_add_u32_e32 v0, s51, v153
	s_add_i32 s59, 0, 0x1c000
	ds_read_b128 v[170:173], v0
	ds_read_b128 v[174:177], v0 offset:1024
	ds_read_b128 v[178:181], v0 offset:2048
	ds_read_b128 v[182:185], v0 offset:3072
	v_add_u32_e32 v0, s59, v153
	ds_read_b128 v[186:189], v0
	ds_read_b128 v[190:193], v0 offset:1024
	ds_read_b128 v[206:209], v0 offset:2048
	ds_read_b128 v[210:213], v0 offset:3072
	s_add_u32 s38, s76, 0x40000
	s_addc_u32 s39, s77, 0
	s_mov_b32 m0, s86
	v_lshl_add_u64 v[252:253], s[38:39], 0, v[136:137]
	ds_read_b128 v[214:217], v167 offset:32768
	ds_read_b128 v[218:221], v167 offset:33792
	ds_read_b128 v[222:225], v167 offset:34816
	ds_read_b128 v[226:229], v167 offset:35840
	ds_read_b128 v[230:233], v167 offset:36864
	ds_read_b128 v[234:237], v167 offset:37888
	ds_read_b128 v[238:241], v167 offset:38912
	ds_read_b128 v[242:245], v167 offset:39936
	global_load_lds_dwordx4 v[252:253], off
	v_lshl_add_u64 v[252:253], s[38:39], 0, v[132:133]
	s_mov_b32 m0, s87
	s_nop 0
	global_load_lds_dwordx4 v[252:253], off
	s_waitcnt vmcnt(8)
	s_waitcnt lgkmcnt(0)
	s_setprio 1
	s_barrier
	v_mfma_f32_16x16x32_bf16 v[126:129], v[170:173], v[214:217], v[126:129]
	v_mfma_f32_16x16x32_bf16 v[122:125], v[178:181], v[214:217], v[122:125]
	v_mfma_f32_16x16x32_bf16 v[110:113], v[170:173], v[222:225], v[110:113]
	v_mfma_f32_16x16x32_bf16 v[106:109], v[178:181], v[222:225], v[106:109]
	v_mfma_f32_16x16x32_bf16 v[94:97], v[170:173], v[230:233], v[94:97]
	v_mfma_f32_16x16x32_bf16 v[90:93], v[178:181], v[230:233], v[90:93]
	v_mfma_f32_16x16x32_bf16 v[78:81], v[170:173], v[238:241], v[78:81]
	v_mfma_f32_16x16x32_bf16 v[74:77], v[178:181], v[238:241], v[74:77]
	v_mfma_f32_16x16x32_bf16 v[126:129], v[174:177], v[218:221], v[126:129]
	v_mfma_f32_16x16x32_bf16 v[122:125], v[182:185], v[218:221], v[122:125]
	v_mfma_f32_16x16x32_bf16 v[110:113], v[174:177], v[226:229], v[110:113]
	v_mfma_f32_16x16x32_bf16 v[106:109], v[182:185], v[226:229], v[106:109]
	v_mfma_f32_16x16x32_bf16 v[94:97], v[174:177], v[234:237], v[94:97]
	v_mfma_f32_16x16x32_bf16 v[90:93], v[182:185], v[234:237], v[90:93]
	v_mfma_f32_16x16x32_bf16 v[78:81], v[174:177], v[242:245], v[78:81]
	v_mfma_f32_16x16x32_bf16 v[74:77], v[182:185], v[242:245], v[74:77]
	v_mfma_f32_16x16x32_bf16 v[118:121], v[186:189], v[214:217], v[118:121]
	v_mfma_f32_16x16x32_bf16 v[114:117], v[206:209], v[214:217], v[114:117]
	v_mfma_f32_16x16x32_bf16 v[102:105], v[186:189], v[222:225], v[102:105]
	v_mfma_f32_16x16x32_bf16 v[98:101], v[206:209], v[222:225], v[98:101]
	v_mfma_f32_16x16x32_bf16 v[86:89], v[186:189], v[230:233], v[86:89]
	v_mfma_f32_16x16x32_bf16 v[82:85], v[206:209], v[230:233], v[82:85]
	v_mfma_f32_16x16x32_bf16 v[70:73], v[186:189], v[238:241], v[70:73]
	v_mfma_f32_16x16x32_bf16 v[66:69], v[206:209], v[238:241], v[66:69]
	v_mfma_f32_16x16x32_bf16 v[118:121], v[190:193], v[218:221], v[118:121]
	v_mfma_f32_16x16x32_bf16 v[114:117], v[210:213], v[218:221], v[114:117]
	v_mfma_f32_16x16x32_bf16 v[102:105], v[190:193], v[226:229], v[102:105]
	v_mfma_f32_16x16x32_bf16 v[98:101], v[210:213], v[226:229], v[98:101]
	v_mfma_f32_16x16x32_bf16 v[86:89], v[190:193], v[234:237], v[86:89]
	v_mfma_f32_16x16x32_bf16 v[82:85], v[210:213], v[234:237], v[82:85]
	s_setprio 0
	v_mfma_f32_16x16x32_bf16 v[70:73], v[190:193], v[242:245], v[70:73]
	v_mfma_f32_16x16x32_bf16 v[66:69], v[210:213], v[242:245], v[66:69]
	s_barrier
; #define PG8_STAGE(bufoff, gbase, voff) do { _Pragma("unroll") for (int _i = 0; _i < 2; ++_i) \
;         __builtin_amdgcn_global_load_lds((const unsigned*)((const char*)(gbase) + (voff)[_i]), (PG8_LAS unsigned*)(lds + (bufoff) + ldsw + _i * 8192), 16, 0, 0); } while (0)
; #define PG8_LDA(dst, b, h) do { _Pragma("unroll") for (int m = 0; m < 4; ++m) _Pragma("unroll") for (int k = 0; k < 2; ++k) dst[m][k] = *(const PG8_LAS bf16x8*)(lds + PG8_SA(b, h) + aoff + m * 2048 + k * 1024); } while (0)
; #define PG8_MMA(ai, bj, At, Bt) do { __builtin_amdgcn_s_setprio(1); _Pragma("unroll") for (int m = 0; m < 4; ++m) _Pragma("unroll") for (int n = 0; n < 2; ++n) _Pragma("unroll") for (int k = 0; k < 2; ++k) \
;         acc[ai][bj][m][n] = __builtin_amdgcn_mfma_f32_16x16x32_bf16(Bt[n][k], At[m][k], acc[ai][bj][m][n], 0, 0, 0); __builtin_amdgcn_s_setprio(0); } while (0)
; #define PG8_WAIT_V(n) asm volatile("s_waitcnt vmcnt(" #n ")" ::: "memory")
; #define PG8_WAIT_L(n) asm volatile("s_waitcnt lgkmcnt(" #n ")" ::: "memory")
; #define PG8_BAR __builtin_amdgcn_s_barrier()
; #define PG8_SCHED __builtin_amdgcn_sched_barrier(0)
; template <class Epi, class Sched, bool ALIGN_EPI = false, bool SP2 = false>
; __device__ __forceinline__ void gemm_phase(PG8_LAS unsigned char* lds, const Gemm g, const Sched& S, const Epi& E, const int tid) {
;     ...
;             PG8_WAIT_V(8); PG8_WAIT_L(0); PG8_BAR; PG8_MMA(0, 0, At, B0); PG8_MMA(0, 1, At, B1); PG8_BAR; PG8_SCHED;
;             PG8_LDA(At, 1, 1); PG8_STAGE(PG8_SB(1, 0), b3, voffB); PG8_STAGE(PG8_SB(1, 1), b3 + hstep, voffB); PG8_STAGE(PG8_SA(1, 0), a3, voffA);
;             PG8_WAIT_V(8); PG8_WAIT_L(0); PG8_BAR; PG8_MMA(1, 0, At, B0); PG8_MMA(1, 1, At, B1); PG8_BAR; PG8_SCHED;
	s_add_i32 s38, s51, s83
	v_lshl_add_u64 v[194:195], v[194:195], 0, s[56:57]
	s_mov_b32 m0, s38
	ds_read_b128 v[214:217], v167 offset:49152
	ds_read_b128 v[218:221], v167 offset:50176
	ds_read_b128 v[222:225], v167 offset:51200
	ds_read_b128 v[226:229], v167 offset:52224
	ds_read_b128 v[230:233], v167 offset:53248
	ds_read_b128 v[234:237], v167 offset:54272
	ds_read_b128 v[238:241], v167 offset:55296
	ds_read_b128 v[242:245], v167 offset:56320
	global_load_lds_dwordx4 v[194:195], off
	s_add_i32 m0, s38, 0x2000
	s_add_u32 s38, s74, 0x40080
	v_lshl_add_u64 v[194:195], v[246:247], 0, s[56:57]
	s_addc_u32 s39, s75, 0
	s_add_i32 s51, s59, s83
	global_load_lds_dwordx4 v[194:195], off
	v_lshl_add_u64 v[194:195], s[38:39], 0, v[134:135]
	s_mov_b32 m0, s51
	s_nop 0
	global_load_lds_dwordx4 v[194:195], off
	v_lshl_add_u64 v[194:195], s[38:39], 0, v[130:131]
	s_add_i32 m0, s51, 0x2000
	s_nop 0
	global_load_lds_dwordx4 v[194:195], off
	v_lshl_add_u64 v[194:195], v[248:249], 0, s[56:57]
	s_mov_b32 m0, s88
	s_nop 0
	global_load_lds_dwordx4 v[194:195], off
	v_lshl_add_u64 v[194:195], v[250:251], 0, s[56:57]
	s_mov_b32 m0, s89
	s_nop 0
	global_load_lds_dwordx4 v[194:195], off
	s_waitcnt vmcnt(8)
	s_waitcnt lgkmcnt(0)
	s_setprio 1
	s_barrier
	v_mfma_f32_16x16x32_bf16 v[62:65], v[170:173], v[214:217], v[62:65]
	v_mfma_f32_16x16x32_bf16 v[58:61], v[178:181], v[214:217], v[58:61]
	v_mfma_f32_16x16x32_bf16 v[46:49], v[170:173], v[222:225], v[46:49]
	v_mfma_f32_16x16x32_bf16 v[42:45], v[178:181], v[222:225], v[42:45]
	v_mfma_f32_16x16x32_bf16 v[30:33], v[170:173], v[230:233], v[30:33]
	v_mfma_f32_16x16x32_bf16 v[26:29], v[178:181], v[230:233], v[26:29]
	v_mfma_f32_16x16x32_bf16 v[14:17], v[170:173], v[238:241], v[14:17]
	v_mfma_f32_16x16x32_bf16 v[10:13], v[178:181], v[238:241], v[10:13]
	v_mfma_f32_16x16x32_bf16 v[62:65], v[174:177], v[218:221], v[62:65]
	v_mfma_f32_16x16x32_bf16 v[58:61], v[182:185], v[218:221], v[58:61]
	v_mfma_f32_16x16x32_bf16 v[46:49], v[174:177], v[226:229], v[46:49]
	v_mfma_f32_16x16x32_bf16 v[42:45], v[182:185], v[226:229], v[42:45]
	v_mfma_f32_16x16x32_bf16 v[30:33], v[174:177], v[234:237], v[30:33]
	v_mfma_f32_16x16x32_bf16 v[26:29], v[182:185], v[234:237], v[26:29]
	v_mfma_f32_16x16x32_bf16 v[14:17], v[174:177], v[242:245], v[14:17]
	v_mfma_f32_16x16x32_bf16 v[10:13], v[182:185], v[242:245], v[10:13]
	v_mfma_f32_16x16x32_bf16 v[54:57], v[186:189], v[214:217], v[54:57]
	v_mfma_f32_16x16x32_bf16 v[50:53], v[206:209], v[214:217], v[50:53]
	v_mfma_f32_16x16x32_bf16 v[38:41], v[186:189], v[222:225], v[38:41]
	v_mfma_f32_16x16x32_bf16 v[34:37], v[206:209], v[222:225], v[34:37]
	v_mfma_f32_16x16x32_bf16 v[22:25], v[186:189], v[230:233], v[22:25]
	v_mfma_f32_16x16x32_bf16 v[18:21], v[206:209], v[230:233], v[18:21]
	v_mfma_f32_16x16x32_bf16 v[6:9], v[186:189], v[238:241], v[6:9]
	v_mfma_f32_16x16x32_bf16 v[2:5], v[206:209], v[238:241], v[2:5]
	v_mfma_f32_16x16x32_bf16 v[54:57], v[190:193], v[218:221], v[54:57]
	v_mfma_f32_16x16x32_bf16 v[50:53], v[210:213], v[218:221], v[50:53]
	v_mfma_f32_16x16x32_bf16 v[38:41], v[190:193], v[226:229], v[38:41]
	v_mfma_f32_16x16x32_bf16 v[34:37], v[210:213], v[226:229], v[34:37]
	v_mfma_f32_16x16x32_bf16 v[22:25], v[190:193], v[234:237], v[22:25]
	v_mfma_f32_16x16x32_bf16 v[18:21], v[210:213], v[234:237], v[18:21]
	s_setprio 0
	v_mfma_f32_16x16x32_bf16 v[6:9], v[190:193], v[242:245], v[6:9]
	v_mfma_f32_16x16x32_bf16 v[2:5], v[210:213], v[242:245], v[2:5]
	s_barrier
	s_add_i32 s50, s50, 2
	s_add_u32 s12, s12, 0x100
	s_addc_u32 s13, s13, 0
	s_cmp_gt_u32 s50, 13
	s_cbranch_scc1 .LBB0_211

; #define PG8_STAGE(bufoff, gbase, voff) do { _Pragma("unroll") for (int _i = 0; _i < 2; ++_i) \
;         __builtin_amdgcn_global_load_lds((const unsigned*)((const char*)(gbase) + (voff)[_i]), (PG8_LAS unsigned*)(lds + (bufoff) + ldsw + _i * 8192), 16, 0, 0); } while (0)
; #define PG8_LDA(dst, b, h) do { _Pragma("unroll") for (int m = 0; m < 4; ++m) _Pragma("unroll") for (int k = 0; k < 2; ++k) dst[m][k] = *(const PG8_LAS bf16x8*)(lds + PG8_SA(b, h) + aoff + m * 2048 + k * 1024); } while (0)
; #define PG8_LDB(dst, b, h) do { _Pragma("unroll") for (int n = 0; n < 2; ++n) _Pragma("unroll") for (int k = 0; k < 2; ++k) dst[n][k] = *(const PG8_LAS bf16x8*)(lds + PG8_SB(b, h) + boff + n * 2048 + k * 1024); } while (0)
; #define PG8_MMA(ai, bj, At, Bt) do { __builtin_amdgcn_s_setprio(1); _Pragma("unroll") for (int m = 0; m < 4; ++m) _Pragma("unroll") for (int n = 0; n < 2; ++n) _Pragma("unroll") for (int k = 0; k < 2; ++k) \
;         acc[ai][bj][m][n] = __builtin_amdgcn_mfma_f32_16x16x32_bf16(Bt[n][k], At[m][k], acc[ai][bj][m][n], 0, 0, 0); __builtin_amdgcn_s_setprio(0); } while (0)
; #define PG8_WAIT_V(n) asm volatile("s_waitcnt vmcnt(" #n ")" ::: "memory")
; #define PG8_WAIT_L(n) asm volatile("s_waitcnt lgkmcnt(" #n ")" ::: "memory")
; #define PG8_BAR __builtin_amdgcn_s_barrier()
; #define PG8_SCHED __builtin_amdgcn_sched_barrier(0)
; template <class Epi, class Sched, bool ALIGN_EPI = false, bool SP2 = false>
; __device__ __forceinline__ void gemm_phase(PG8_LAS unsigned char* lds, const Gemm g, const Sched& S, const Epi& E, const int tid) {
;     ...
;             const char* a2 = last ? nA : cA + (size_t)(t + 2) * kstep; const char* b2 = last ? nB : cB + (size_t)(t + 2) * kstep;
;             const char* a3 = a2 + kstep; const char* b3 = b2 + kstep;
;             if (last && has_next) S.a_ready(nxt);
;             if constexpr (SP2) {
;             PG8_LDB(B0, 0, 0); PG8_LDB(B1, 0, 1); PG8_SCHED; PG8_LDA(At, 0, 0); PG8_STAGE(PG8_SA(1, 1), a1 + hstep, voffA);
;             PG8_WAIT_V(8); PG8_WAIT_L(0); PG8_BAR; PG8_MMA(0, 0, At, B0); PG8_MMA(0, 1, At, B1); PG8_BAR; PG8_SCHED;
;             PG8_LDA(At, 0, 1); PG8_STAGE(PG8_SB(0, 0), b2, voffB); PG8_STAGE(PG8_SB(0, 1), b2 + hstep, voffB); PG8_STAGE(PG8_SA(0, 0), a2, voffA);
;             PG8_WAIT_V(8); PG8_WAIT_L(0); PG8_BAR; PG8_MMA(1, 0, At, B0); PG8_MMA(1, 1, At, B1); PG8_BAR; PG8_SCHED;
.LBB0_618:
	s_add_i32 s85, s70, 2
	s_add_u32 s38, s68, 0x80
	s_addc_u32 s39, s69, 0
	s_add_i32 s59, 0, 0x10000
	s_cmp_eq_u32 s81, s70
	s_cselect_b32 s71, s11, s39
	s_cselect_b32 s70, s10, s38
	s_cselect_b32 s39, s67, s51
	s_cselect_b32 s38, s66, s50
	s_add_i32 s86, 0, 0x14000
	v_add_u32_e32 v142, s59, v205
	v_add_u32_e32 v180, s86, v205
	ds_read_b128 v[130:133], v142
	ds_read_b128 v[134:137], v142 offset:1024
	ds_read_b128 v[138:141], v142 offset:2048
	ds_read_b128 v[142:145], v142 offset:3072
	ds_read_b128 v[146:149], v180
	ds_read_b128 v[150:153], v180 offset:1024
	ds_read_b128 v[176:179], v180 offset:2048
	ds_read_b128 v[180:183], v180 offset:3072
	v_lshl_add_u64 v[192:193], s[68:69], 0, v[172:173]
	s_add_i32 m0, s73, 0xc000
	ds_read_b128 v[184:187], v207
	ds_read_b128 v[188:191], v207 offset:1024
	ds_read_b128 v[208:211], v207 offset:2048
	ds_read_b128 v[212:215], v207 offset:3072
	ds_read_b128 v[216:219], v207 offset:4096
	ds_read_b128 v[220:223], v207 offset:5120
	ds_read_b128 v[224:227], v207 offset:6144
	ds_read_b128 v[228:231], v207 offset:7168
	global_load_lds_dwordx4 v[192:193], off
	v_lshl_add_u64 v[192:193], s[68:69], 0, v[174:175]
	s_add_i32 m0, s73, 0xe000
	s_nop 0
	global_load_lds_dwordx4 v[192:193], off
	s_waitcnt vmcnt(8)
	s_waitcnt lgkmcnt(0)
	s_setprio 1
	s_barrier
	v_mfma_f32_16x16x32_bf16 v[126:129], v[130:133], v[184:187], v[126:129]
	v_mfma_f32_16x16x32_bf16 v[122:125], v[138:141], v[184:187], v[122:125]
	v_mfma_f32_16x16x32_bf16 v[110:113], v[130:133], v[208:211], v[110:113]
	v_mfma_f32_16x16x32_bf16 v[106:109], v[138:141], v[208:211], v[106:109]
	v_mfma_f32_16x16x32_bf16 v[94:97], v[130:133], v[216:219], v[94:97]
	v_mfma_f32_16x16x32_bf16 v[90:93], v[138:141], v[216:219], v[90:93]
	v_mfma_f32_16x16x32_bf16 v[78:81], v[130:133], v[224:227], v[78:81]
	v_mfma_f32_16x16x32_bf16 v[74:77], v[138:141], v[224:227], v[74:77]
	v_mfma_f32_16x16x32_bf16 v[126:129], v[134:137], v[188:191], v[126:129]
	v_mfma_f32_16x16x32_bf16 v[122:125], v[142:145], v[188:191], v[122:125]
	v_mfma_f32_16x16x32_bf16 v[110:113], v[134:137], v[212:215], v[110:113]
	v_mfma_f32_16x16x32_bf16 v[106:109], v[142:145], v[212:215], v[106:109]
	v_mfma_f32_16x16x32_bf16 v[94:97], v[134:137], v[220:223], v[94:97]
	v_mfma_f32_16x16x32_bf16 v[90:93], v[142:145], v[220:223], v[90:93]
	v_mfma_f32_16x16x32_bf16 v[78:81], v[134:137], v[228:231], v[78:81]
	v_mfma_f32_16x16x32_bf16 v[74:77], v[142:145], v[228:231], v[74:77]
	v_mfma_f32_16x16x32_bf16 v[118:121], v[146:149], v[184:187], v[118:121]
	v_mfma_f32_16x16x32_bf16 v[114:117], v[176:179], v[184:187], v[114:117]
	v_mfma_f32_16x16x32_bf16 v[102:105], v[146:149], v[208:211], v[102:105]
	v_mfma_f32_16x16x32_bf16 v[98:101], v[176:179], v[208:211], v[98:101]
	v_mfma_f32_16x16x32_bf16 v[86:89], v[146:149], v[216:219], v[86:89]
	v_mfma_f32_16x16x32_bf16 v[82:85], v[176:179], v[216:219], v[82:85]
	v_mfma_f32_16x16x32_bf16 v[70:73], v[146:149], v[224:227], v[70:73]
	v_mfma_f32_16x16x32_bf16 v[66:69], v[176:179], v[224:227], v[66:69]
	v_mfma_f32_16x16x32_bf16 v[118:121], v[150:153], v[188:191], v[118:121]
	v_mfma_f32_16x16x32_bf16 v[114:117], v[180:183], v[188:191], v[114:117]
	v_mfma_f32_16x16x32_bf16 v[102:105], v[150:153], v[212:215], v[102:105]
	v_mfma_f32_16x16x32_bf16 v[98:101], v[180:183], v[212:215], v[98:101]
	v_mfma_f32_16x16x32_bf16 v[86:89], v[150:153], v[220:223], v[86:89]
	v_mfma_f32_16x16x32_bf16 v[82:85], v[180:183], v[220:223], v[82:85]
	s_setprio 0
	v_mfma_f32_16x16x32_bf16 v[70:73], v[150:153], v[228:231], v[70:73]
	v_mfma_f32_16x16x32_bf16 v[66:69], v[180:183], v[228:231], v[66:69]
	s_barrier
	s_add_i32 s59, s59, s72
	v_lshl_add_u64 v[192:193], s[38:39], 0, v[0:1]
	s_mov_b32 m0, s59
	ds_read_b128 v[184:187], v207 offset:16384
	ds_read_b128 v[188:191], v207 offset:17408
	ds_read_b128 v[208:211], v207 offset:18432
	ds_read_b128 v[212:215], v207 offset:19456
	ds_read_b128 v[216:219], v207 offset:20480
	ds_read_b128 v[220:223], v207 offset:21504
	ds_read_b128 v[224:227], v207 offset:22528
	ds_read_b128 v[228:231], v207 offset:23552
	global_load_lds_dwordx4 v[192:193], off
	s_add_i32 m0, s59, 0x2000
	v_lshl_add_u64 v[194:195], s[38:39], 0, v[166:167]
	s_add_u32 s38, s38, s14
	s_addc_u32 s39, s39, 0
	s_add_i32 s59, s86, s72
	global_load_lds_dwordx4 v[194:195], off
	v_lshl_add_u64 v[232:233], s[38:39], 0, v[0:1]
	s_mov_b32 m0, s59
	v_lshl_add_u64 v[234:235], s[38:39], 0, v[166:167]
	global_load_lds_dwordx4 v[232:233], off
	s_add_i32 m0, s59, 0x2000
	v_lshl_add_u64 v[236:237], s[70:71], 0, v[170:171]
	global_load_lds_dwordx4 v[234:235], off
	s_mov_b32 m0, s73
	v_lshl_add_u64 v[238:239], s[70:71], 0, v[168:169]
	global_load_lds_dwordx4 v[236:237], off
	s_mov_b32 m0, s74
	s_nop 0
	global_load_lds_dwordx4 v[238:239], off
	s_waitcnt vmcnt(8)
	s_waitcnt lgkmcnt(0)
	s_setprio 1
	s_barrier
; #define PG8_STAGE(bufoff, gbase, voff) do { _Pragma("unroll") for (int _i = 0; _i < 2; ++_i) \
;         __builtin_amdgcn_global_load_lds((const unsigned*)((const char*)(gbase) + (voff)[_i]), (PG8_LAS unsigned*)(lds + (bufoff) + ldsw + _i * 8192), 16, 0, 0); } while (0)
; #define PG8_LDA(dst, b, h) do { _Pragma("unroll") for (int m = 0; m < 4; ++m) _Pragma("unroll") for (int k = 0; k < 2; ++k) dst[m][k] = *(const PG8_LAS bf16x8*)(lds + PG8_SA(b, h) + aoff + m * 2048 + k * 1024); } while (0)
; #define PG8_LDB(dst, b, h) do { _Pragma("unroll") for (int n = 0; n < 2; ++n) _Pragma("unroll") for (int k = 0; k < 2; ++k) dst[n][k] = *(const PG8_LAS bf16x8*)(lds + PG8_SB(b, h) + boff + n * 2048 + k * 1024); } while (0)
; #define PG8_MMA(ai, bj, At, Bt) do { __builtin_amdgcn_s_setprio(1); _Pragma("unroll") for (int m = 0; m < 4; ++m) _Pragma("unroll") for (int n = 0; n < 2; ++n) _Pragma("unroll") for (int k = 0; k < 2; ++k) \
;         acc[ai][bj][m][n] = __builtin_amdgcn_mfma_f32_16x16x32_bf16(Bt[n][k], At[m][k], acc[ai][bj][m][n], 0, 0, 0); __builtin_amdgcn_s_setprio(0); } while (0)
; #define PG8_WAIT_V(n) asm volatile("s_waitcnt vmcnt(" #n ")" ::: "memory")
; #define PG8_WAIT_L(n) asm volatile("s_waitcnt lgkmcnt(" #n ")" ::: "memory")
; #define PG8_BAR __builtin_amdgcn_s_barrier()
; #define PG8_SCHED __builtin_amdgcn_sched_barrier(0)
; template <class Epi, class Sched, bool ALIGN_EPI = false, bool SP2 = false>
; __device__ __forceinline__ void gemm_phase(PG8_LAS unsigned char* lds, const Gemm g, const Sched& S, const Epi& E, const int tid) {
;     ...
;             PG8_WAIT_V(8); PG8_WAIT_L(0); PG8_BAR; PG8_MMA(1, 0, At, B0); PG8_MMA(1, 1, At, B1); PG8_BAR; PG8_SCHED;
;             PG8_LDB(B0, 1, 0); PG8_LDB(B1, 1, 1); PG8_SCHED; PG8_LDA(At, 1, 0); PG8_STAGE(PG8_SA(0, 1), a2 + hstep, voffA);
;             PG8_WAIT_V(8); PG8_WAIT_L(0); PG8_BAR; PG8_MMA(0, 0, At, B0); PG8_MMA(0, 1, At, B1); PG8_BAR; PG8_SCHED;
	v_mfma_f32_16x16x32_bf16 v[62:65], v[130:133], v[184:187], v[62:65]
	v_mfma_f32_16x16x32_bf16 v[58:61], v[138:141], v[184:187], v[58:61]
	v_mfma_f32_16x16x32_bf16 v[46:49], v[130:133], v[208:211], v[46:49]
	v_mfma_f32_16x16x32_bf16 v[42:45], v[138:141], v[208:211], v[42:45]
	v_mfma_f32_16x16x32_bf16 v[30:33], v[130:133], v[216:219], v[30:33]
	v_mfma_f32_16x16x32_bf16 v[26:29], v[138:141], v[216:219], v[26:29]
	v_mfma_f32_16x16x32_bf16 v[14:17], v[130:133], v[224:227], v[14:17]
	v_mfma_f32_16x16x32_bf16 v[10:13], v[138:141], v[224:227], v[10:13]
	v_mfma_f32_16x16x32_bf16 v[62:65], v[134:137], v[188:191], v[62:65]
	v_mfma_f32_16x16x32_bf16 v[58:61], v[142:145], v[188:191], v[58:61]
	v_mfma_f32_16x16x32_bf16 v[46:49], v[134:137], v[212:215], v[46:49]
	v_mfma_f32_16x16x32_bf16 v[42:45], v[142:145], v[212:215], v[42:45]
	v_mfma_f32_16x16x32_bf16 v[30:33], v[134:137], v[220:223], v[30:33]
	v_mfma_f32_16x16x32_bf16 v[26:29], v[142:145], v[220:223], v[26:29]
	v_mfma_f32_16x16x32_bf16 v[14:17], v[134:137], v[228:231], v[14:17]
	v_mfma_f32_16x16x32_bf16 v[10:13], v[142:145], v[228:231], v[10:13]
	v_mfma_f32_16x16x32_bf16 v[54:57], v[146:149], v[184:187], v[54:57]
	v_mfma_f32_16x16x32_bf16 v[50:53], v[176:179], v[184:187], v[50:53]
	v_mfma_f32_16x16x32_bf16 v[38:41], v[146:149], v[208:211], v[38:41]
	v_mfma_f32_16x16x32_bf16 v[34:37], v[176:179], v[208:211], v[34:37]
	v_mfma_f32_16x16x32_bf16 v[22:25], v[146:149], v[216:219], v[22:25]
	v_mfma_f32_16x16x32_bf16 v[18:21], v[176:179], v[216:219], v[18:21]
	v_mfma_f32_16x16x32_bf16 v[6:9], v[146:149], v[224:227], v[6:9]
	v_mfma_f32_16x16x32_bf16 v[2:5], v[176:179], v[224:227], v[2:5]
	v_mfma_f32_16x16x32_bf16 v[54:57], v[150:153], v[188:191], v[54:57]
	v_mfma_f32_16x16x32_bf16 v[50:53], v[180:183], v[188:191], v[50:53]
	v_mfma_f32_16x16x32_bf16 v[38:41], v[150:153], v[212:215], v[38:41]
	v_mfma_f32_16x16x32_bf16 v[34:37], v[180:183], v[212:215], v[34:37]
	v_mfma_f32_16x16x32_bf16 v[22:25], v[150:153], v[220:223], v[22:25]
	v_mfma_f32_16x16x32_bf16 v[18:21], v[180:183], v[220:223], v[18:21]
	s_setprio 0
	v_mfma_f32_16x16x32_bf16 v[6:9], v[150:153], v[228:231], v[6:9]
	v_mfma_f32_16x16x32_bf16 v[2:5], v[180:183], v[228:231], v[2:5]
	s_barrier
	s_add_i32 s59, 0, 0x18000
	s_add_i32 s86, 0, 0x1c000
	v_add_u32_e32 v142, s59, v205
	v_add_u32_e32 v180, s86, v205
	ds_read_b128 v[130:133], v142
	ds_read_b128 v[134:137], v142 offset:1024
	ds_read_b128 v[138:141], v142 offset:2048
	ds_read_b128 v[142:145], v142 offset:3072
	ds_read_b128 v[146:149], v180
	ds_read_b128 v[150:153], v180 offset:1024
	ds_read_b128 v[176:179], v180 offset:2048
	ds_read_b128 v[180:183], v180 offset:3072
	s_add_u32 s38, s70, s14
	s_addc_u32 s39, s71, 0
	s_mov_b32 m0, s75
	v_lshl_add_u64 v[240:241], s[38:39], 0, v[170:171]
	ds_read_b128 v[184:187], v207 offset:32768
	ds_read_b128 v[188:191], v207 offset:33792
	ds_read_b128 v[208:211], v207 offset:34816
	ds_read_b128 v[212:215], v207 offset:35840
	ds_read_b128 v[216:219], v207 offset:36864
	ds_read_b128 v[220:223], v207 offset:37888
	ds_read_b128 v[224:227], v207 offset:38912
	ds_read_b128 v[228:231], v207 offset:39936
	global_load_lds_dwordx4 v[240:241], off
	v_lshl_add_u64 v[240:241], s[38:39], 0, v[168:169]
	s_mov_b32 m0, s76
	s_nop 0
	global_load_lds_dwordx4 v[240:241], off
	s_waitcnt vmcnt(8)
	s_waitcnt lgkmcnt(0)
	s_setprio 1
	s_barrier
	v_mfma_f32_16x16x32_bf16 v[126:129], v[130:133], v[184:187], v[126:129]
	v_mfma_f32_16x16x32_bf16 v[122:125], v[138:141], v[184:187], v[122:125]
	v_mfma_f32_16x16x32_bf16 v[110:113], v[130:133], v[208:211], v[110:113]
	v_mfma_f32_16x16x32_bf16 v[106:109], v[138:141], v[208:211], v[106:109]
	v_mfma_f32_16x16x32_bf16 v[94:97], v[130:133], v[216:219], v[94:97]
	v_mfma_f32_16x16x32_bf16 v[90:93], v[138:141], v[216:219], v[90:93]
	v_mfma_f32_16x16x32_bf16 v[78:81], v[130:133], v[224:227], v[78:81]
	v_mfma_f32_16x16x32_bf16 v[74:77], v[138:141], v[224:227], v[74:77]
	v_mfma_f32_16x16x32_bf16 v[126:129], v[134:137], v[188:191], v[126:129]
	v_mfma_f32_16x16x32_bf16 v[122:125], v[142:145], v[188:191], v[122:125]
	v_mfma_f32_16x16x32_bf16 v[110:113], v[134:137], v[212:215], v[110:113]
	v_mfma_f32_16x16x32_bf16 v[106:109], v[142:145], v[212:215], v[106:109]
	v_mfma_f32_16x16x32_bf16 v[94:97], v[134:137], v[220:223], v[94:97]
	v_mfma_f32_16x16x32_bf16 v[90:93], v[142:145], v[220:223], v[90:93]
	v_mfma_f32_16x16x32_bf16 v[78:81], v[134:137], v[228:231], v[78:81]
	v_mfma_f32_16x16x32_bf16 v[74:77], v[142:145], v[228:231], v[74:77]
	v_mfma_f32_16x16x32_bf16 v[118:121], v[146:149], v[184:187], v[118:121]
	v_mfma_f32_16x16x32_bf16 v[114:117], v[176:179], v[184:187], v[114:117]
	v_mfma_f32_16x16x32_bf16 v[102:105], v[146:149], v[208:211], v[102:105]
	v_mfma_f32_16x16x32_bf16 v[98:101], v[176:179], v[208:211], v[98:101]
	v_mfma_f32_16x16x32_bf16 v[86:89], v[146:149], v[216:219], v[86:89]
	v_mfma_f32_16x16x32_bf16 v[82:85], v[176:179], v[216:219], v[82:85]
	v_mfma_f32_16x16x32_bf16 v[70:73], v[146:149], v[224:227], v[70:73]
	v_mfma_f32_16x16x32_bf16 v[66:69], v[176:179], v[224:227], v[66:69]
	v_mfma_f32_16x16x32_bf16 v[118:121], v[150:153], v[188:191], v[118:121]
	v_mfma_f32_16x16x32_bf16 v[114:117], v[180:183], v[188:191], v[114:117]
	v_mfma_f32_16x16x32_bf16 v[102:105], v[150:153], v[212:215], v[102:105]
	v_mfma_f32_16x16x32_bf16 v[98:101], v[180:183], v[212:215], v[98:101]
	v_mfma_f32_16x16x32_bf16 v[86:89], v[150:153], v[220:223], v[86:89]
	v_mfma_f32_16x16x32_bf16 v[82:85], v[180:183], v[220:223], v[82:85]
	s_setprio 0
	v_mfma_f32_16x16x32_bf16 v[70:73], v[150:153], v[228:231], v[70:73]
	v_mfma_f32_16x16x32_bf16 v[66:69], v[180:183], v[228:231], v[66:69]
	s_barrier
; #define PG8_STAGE(bufoff, gbase, voff) do { _Pragma("unroll") for (int _i = 0; _i < 2; ++_i) \
;         __builtin_amdgcn_global_load_lds((const unsigned*)((const char*)(gbase) + (voff)[_i]), (PG8_LAS unsigned*)(lds + (bufoff) + ldsw + _i * 8192), 16, 0, 0); } while (0)
; #define PG8_LDA(dst, b, h) do { _Pragma("unroll") for (int m = 0; m < 4; ++m) _Pragma("unroll") for (int k = 0; k < 2; ++k) dst[m][k] = *(const PG8_LAS bf16x8*)(lds + PG8_SA(b, h) + aoff + m * 2048 + k * 1024); } while (0)
; #define PG8_MMA(ai, bj, At, Bt) do { __builtin_amdgcn_s_setprio(1); _Pragma("unroll") for (int m = 0; m < 4; ++m) _Pragma("unroll") for (int n = 0; n < 2; ++n) _Pragma("unroll") for (int k = 0; k < 2; ++k) \
;         acc[ai][bj][m][n] = __builtin_amdgcn_mfma_f32_16x16x32_bf16(Bt[n][k], At[m][k], acc[ai][bj][m][n], 0, 0, 0); __builtin_amdgcn_s_setprio(0); } while (0)
; #define PG8_WAIT_V(n) asm volatile("s_waitcnt vmcnt(" #n ")" ::: "memory")
; #define PG8_WAIT_L(n) asm volatile("s_waitcnt lgkmcnt(" #n ")" ::: "memory")
; #define PG8_BAR __builtin_amdgcn_s_barrier()
; #define PG8_SCHED __builtin_amdgcn_sched_barrier(0)
; template <class Epi, class Sched, bool ALIGN_EPI = false, bool SP2 = false>
; __device__ __forceinline__ void gemm_phase(PG8_LAS unsigned char* lds, const Gemm g, const Sched& S, const Epi& E, const int tid) {
;     ...
;             PG8_LDA(At, 1, 1); PG8_STAGE(PG8_SB(1, 0), b3, voffB); PG8_STAGE(PG8_SB(1, 1), b3 + hstep, voffB); PG8_STAGE(PG8_SA(1, 0), a3, voffA);
;             PG8_WAIT_V(8); PG8_WAIT_L(0); PG8_BAR; PG8_MMA(1, 0, At, B0); PG8_MMA(1, 1, At, B1); PG8_BAR; PG8_SCHED;
	s_add_i32 s38, s59, s72
	v_lshl_add_u64 v[192:193], v[192:193], 0, s[56:57]
	s_mov_b32 m0, s38
	ds_read_b128 v[184:187], v207 offset:49152
	ds_read_b128 v[188:191], v207 offset:50176
	ds_read_b128 v[208:211], v207 offset:51200
	ds_read_b128 v[212:215], v207 offset:52224
	ds_read_b128 v[216:219], v207 offset:53248
	ds_read_b128 v[220:223], v207 offset:54272
	ds_read_b128 v[224:227], v207 offset:55296
	ds_read_b128 v[228:231], v207 offset:56320
	global_load_lds_dwordx4 v[192:193], off
	v_lshl_add_u64 v[192:193], v[194:195], 0, s[56:57]
	s_add_i32 m0, s38, 0x2000
	s_add_i32 s38, s86, s72
	global_load_lds_dwordx4 v[192:193], off
	v_lshl_add_u64 v[192:193], v[232:233], 0, s[56:57]
	s_mov_b32 m0, s38
	s_nop 0
	global_load_lds_dwordx4 v[192:193], off
	v_lshl_add_u64 v[192:193], v[234:235], 0, s[56:57]
	s_add_i32 m0, s38, 0x2000
	s_nop 0
	global_load_lds_dwordx4 v[192:193], off
	v_lshl_add_u64 v[192:193], v[236:237], 0, s[56:57]
	s_mov_b32 m0, s79
	s_nop 0
	global_load_lds_dwordx4 v[192:193], off
	v_lshl_add_u64 v[192:193], v[238:239], 0, s[56:57]
	s_mov_b32 m0, s80
	s_nop 0
	global_load_lds_dwordx4 v[192:193], off
	s_waitcnt vmcnt(8)
	s_waitcnt lgkmcnt(0)
	s_setprio 1
	s_barrier
	v_mfma_f32_16x16x32_bf16 v[62:65], v[130:133], v[184:187], v[62:65]
	v_mfma_f32_16x16x32_bf16 v[58:61], v[138:141], v[184:187], v[58:61]
	v_mfma_f32_16x16x32_bf16 v[46:49], v[130:133], v[208:211], v[46:49]
	v_mfma_f32_16x16x32_bf16 v[42:45], v[138:141], v[208:211], v[42:45]
	v_mfma_f32_16x16x32_bf16 v[30:33], v[130:133], v[216:219], v[30:33]
	v_mfma_f32_16x16x32_bf16 v[26:29], v[138:141], v[216:219], v[26:29]
	v_mfma_f32_16x16x32_bf16 v[14:17], v[130:133], v[224:227], v[14:17]
	v_mfma_f32_16x16x32_bf16 v[10:13], v[138:141], v[224:227], v[10:13]
	v_mfma_f32_16x16x32_bf16 v[62:65], v[134:137], v[188:191], v[62:65]
	v_mfma_f32_16x16x32_bf16 v[58:61], v[142:145], v[188:191], v[58:61]
	v_mfma_f32_16x16x32_bf16 v[46:49], v[134:137], v[212:215], v[46:49]
	v_mfma_f32_16x16x32_bf16 v[42:45], v[142:145], v[212:215], v[42:45]
	v_mfma_f32_16x16x32_bf16 v[30:33], v[134:137], v[220:223], v[30:33]
	v_mfma_f32_16x16x32_bf16 v[26:29], v[142:145], v[220:223], v[26:29]
	v_mfma_f32_16x16x32_bf16 v[14:17], v[134:137], v[228:231], v[14:17]
	v_mfma_f32_16x16x32_bf16 v[10:13], v[142:145], v[228:231], v[10:13]
	v_mfma_f32_16x16x32_bf16 v[54:57], v[146:149], v[184:187], v[54:57]
	v_mfma_f32_16x16x32_bf16 v[50:53], v[176:179], v[184:187], v[50:53]
	v_mfma_f32_16x16x32_bf16 v[38:41], v[146:149], v[208:211], v[38:41]
	v_mfma_f32_16x16x32_bf16 v[34:37], v[176:179], v[208:211], v[34:37]
	v_mfma_f32_16x16x32_bf16 v[22:25], v[146:149], v[216:219], v[22:25]
	v_mfma_f32_16x16x32_bf16 v[18:21], v[176:179], v[216:219], v[18:21]
	v_mfma_f32_16x16x32_bf16 v[6:9], v[146:149], v[224:227], v[6:9]
	v_mfma_f32_16x16x32_bf16 v[2:5], v[176:179], v[224:227], v[2:5]
	v_mfma_f32_16x16x32_bf16 v[54:57], v[150:153], v[188:191], v[54:57]
	v_mfma_f32_16x16x32_bf16 v[50:53], v[180:183], v[188:191], v[50:53]
	v_mfma_f32_16x16x32_bf16 v[38:41], v[150:153], v[212:215], v[38:41]
	v_mfma_f32_16x16x32_bf16 v[34:37], v[180:183], v[212:215], v[34:37]
	v_mfma_f32_16x16x32_bf16 v[22:25], v[150:153], v[220:223], v[22:25]
	v_mfma_f32_16x16x32_bf16 v[18:21], v[180:183], v[220:223], v[18:21]
	s_setprio 0
	v_mfma_f32_16x16x32_bf16 v[6:9], v[150:153], v[228:231], v[6:9]
	v_mfma_f32_16x16x32_bf16 v[2:5], v[180:183], v[228:231], v[2:5]
	s_barrier
	s_add_u32 s68, s68, 0x100
	s_addc_u32 s69, s69, 0
	s_add_u32 s50, s50, 0x100
	s_addc_u32 s51, s51, 0
	s_cmp_ge_u32 s85, s78
	s_mov_b32 s70, s85
	s_cbranch_scc0 .LBB0_618
	s_and_b64 vcc, exec, s[22:23]
	s_cbranch_vccz .LBB0_621
	s_barrier
